# memory attention V^T tile interleaved for ds_read_b128 fragments (as prompt attention)
# baseline (speedup 1.0000x reference)
.LBB0_1798:
	s_andn2_b64 vcc, exec, s[2:3]
	v_xor_b32_e32 v132, 32, v229
	s_cbranch_vccnz .LBB0_1856
	s_add_u32 s38, s4, 0x2d7da000
	s_addc_u32 s39, s5, 0
	s_add_u32 s40, s4, 0x3efda000
	s_addc_u32 s41, s5, 0
	s_add_u32 s42, s4, 0x403da000
	v_cmp_lt_i32_e32 vcc, v130, v131
	s_addc_u32 s43, s5, 0
	s_add_u32 s44, s4, 0x2b552000
	v_cndmask_b32_e32 v2, v229, v130, vcc
	v_cmp_lt_i32_e32 vcc, v132, v131
	v_lshlrev_b32_e32 v85, 2, v2
	s_addc_u32 s45, s5, 0
	v_cndmask_b32_e32 v2, v229, v132, vcc
	s_sub_i32 s2, s7, 32
	v_lshlrev_b32_e32 v87, 2, v2
	v_and_b32_e32 v2, 15, v0
	v_bfe_u32 v3, v0, 4, 2
	s_and_b64 s[0:1], s[0:1], exec
	v_mul_u32_u24_e32 v8, 0x110, v2
	v_mul_u32_u24_e32 v2, 0x90, v2
	v_lshlrev_b32_e32 v84, 3, v3
	v_lshlrev_b32_e32 v6, 3, v0
	s_cselect_b32 s46, s2, s7
	s_ashr_i32 s0, s6, 2
	v_and_b32_e32 v4, 48, v0
	v_lshl_add_u32 v114, v84, 1, v2
	v_ashrrev_i32_e32 v2, 3, v0
	s_movk_i32 s6, 0x90
	v_and_b32_e32 v86, 56, v6
	v_add_u32_e32 v9, 0x200, v0
	v_add_u32_e32 v5, 0, v4
	v_lshlrev_b32_e32 v4, 2, v3
	v_mul_lo_u32 v3, v2, s6
	v_lshlrev_b32_e32 v7, 1, v86
	v_ashrrev_i32_e32 v6, 3, v9
	v_add3_u32 v118, 0, v3, v7
	v_mul_lo_u32 v3, v6, s6
	v_add3_u32 v119, 0, v3, v7
	v_and_b32_e32 v7, 1, v0
	v_lshl_add_u32 v118, v7, 4, v118
	v_lshl_add_u32 v119, v7, 4, v119
	v_bfe_u32 v7, v0, 1, 1
	v_mul_u32_u24_e32 v7, 24, v7
	v_sub_u32_e32 v118, v118, v7
	v_sub_u32_e32 v119, v119, v7
	v_ashrrev_i32_e32 v3, 31, v2
	v_lshlrev_b64 v[88:89], 9, v[2:3]
	v_ashrrev_i32_e32 v2, 31, v0
	v_lshrrev_b32_e32 v2, 28, v2
	v_add_u32_e32 v3, v0, v2
	v_ashrrev_i32_e32 v7, 31, v6
	v_ashrrev_i32_e32 v2, 4, v3
	s_movk_i32 s6, 0x110
	v_lshlrev_b64 v[90:91], 9, v[6:7]
	v_mul_lo_u32 v6, v2, s6
	v_add_u32_e32 v120, 0, v6
	v_ashrrev_i32_e32 v6, 31, v9
	v_lshrrev_b32_e32 v6, 28, v6
	v_and_b32_e32 v3, -16, v3
	v_add_u32_e32 v7, v9, v6
	v_sub_u32_e32 v3, v0, v3
	v_ashrrev_i32_e32 v6, 4, v7
	v_and_b32_e32 v7, -16, v7
	v_lshlrev_b32_e32 v121, 4, v3
	v_sub_u32_e32 v7, v9, v7
	v_lshlrev_b32_e32 v92, 3, v3
	v_ashrrev_i32_e32 v3, 31, v2
	s_movk_i32 s2, 0x200
	v_lshlrev_b32_e32 v123, 4, v7
	v_ashrrev_i32_e32 v93, 31, v92
	v_lshlrev_b32_e32 v94, 3, v7
	v_lshlrev_b64 v[98:99], 8, v[2:3]
	v_ashrrev_i32_e32 v7, 31, v6
	v_bfi_b32 v82, -16, s0, v0
	v_cmp_gt_i32_e64 s[0:1], s95, v0
	v_cmp_gt_i32_e64 s[2:3], s2, v0
	v_mul_lo_u32 v10, v6, s6
	v_ashrrev_i32_e32 v95, 31, v94
	v_lshlrev_b64 v[100:101], 8, v[6:7]
	v_lshl_add_u64 v[2:3], v[92:93], 1, v[98:99]
	s_mov_b64 s[6:7], 0x3efde000
	v_lshlrev_b32_e32 v0, 4, v0
	v_readlane_b32 s12, v253, 36
	v_lshl_add_u64 v[102:103], v[2:3], 0, s[6:7]
	v_lshl_add_u64 v[2:3], v[94:95], 1, v[100:101]
	v_and_b32_e32 v0, 0x70, v0
	v_readlane_b32 s13, v253, 37
	v_lshl_add_u64 v[104:105], v[2:3], 0, s[6:7]
	v_or_b32_e32 v2, v88, v0
	v_mov_b32_e32 v3, v89
	s_mov_b64 s[6:7], 0x403da080
	s_mov_b32 s13, s29
	v_lshl_add_u64 v[106:107], v[2:3], 0, s[6:7]
	v_or_b32_e32 v2, v90, v0
	v_mov_b32_e32 v3, v91
	s_mul_i32 s47, s12, 40
	v_ashrrev_i32_e32 v83, 31, v82
	v_writelane_b32 v253, s12, 36
	v_lshl_add_u64 v[108:109], v[2:3], 0, s[6:7]
	v_mov_b32_e32 v2, 0
	v_mov_b32_e32 v58, 0
	v_add_u32_e32 v115, 0x900, v114
	v_add_u32_e32 v116, 0x1200, v114
	v_add_u32_e32 v117, 0x1b00, v114
	v_add_u32_e32 v122, 0, v10
	v_lshlrev_b64 v[96:97], 10, v[82:83]
	v_writelane_b32 v253, s13, 37
	s_mov_b64 s[18:19], 0
	v_lshlrev_b32_e32 v110, 1, v4
	v_add_u32_e32 v83, v5, v8
	v_mov_b32_e32 v59, v58
	v_mov_b32_e32 v60, v58
	v_mov_b32_e32 v61, v58
	v_mov_b32_e32 v66, v58
	v_mov_b32_e32 v67, v58
	v_mov_b32_e32 v68, v58
	v_mov_b32_e32 v69, v58
	v_mov_b32_e32 v74, v58
	v_mov_b32_e32 v75, v58
	v_mov_b32_e32 v76, v58
	v_mov_b32_e32 v77, v58
	v_mov_b32_e32 v78, v58
	v_mov_b32_e32 v79, v58
	v_mov_b32_e32 v80, v58
	v_mov_b32_e32 v81, v58
	v_mov_b32_e32 v3, v2
	v_mov_b32_e32 v4, v2
	v_mov_b32_e32 v5, v2
	v_mov_b32_e32 v6, v2
	v_mov_b32_e32 v7, v2
	v_mov_b32_e32 v8, v2
	v_mov_b32_e32 v9, v2
	v_mov_b32_e32 v10, v2
	v_mov_b32_e32 v11, v2
	v_mov_b32_e32 v12, v2
	v_mov_b32_e32 v13, v2
	v_mov_b32_e32 v14, v2
	v_mov_b32_e32 v15, v2
	v_mov_b32_e32 v16, v2
	v_mov_b32_e32 v17, v2
	s_branch .LBB0_1801

.LBB0_1829:
	s_or_b64 exec, exec, s[16:17]
	s_waitcnt vmcnt(1)
	ds_write_b64 v118, v[10:11] offset:17408
	ds_write_b64 v118, v[12:13] offset:17424
	s_waitcnt vmcnt(0)
	ds_write_b64 v119, v[14:15] offset:17408
	ds_write_b64 v119, v[16:17] offset:17424
	s_waitcnt lgkmcnt(0)
	s_barrier
	s_and_saveexec_b64 s[16:17], s[0:1]
	s_cbranch_execz .LBB0_1831
	v_lshl_add_u64 v[2:3], s[4:5], 0, v[58:59]
	global_load_dwordx4 v[2:5], v[2:3], off

.LBB0_1833:
	s_or_b64 exec, exec, s[16:17]
	v_lshl_add_u64 v[10:11], s[4:5], 0, v[66:67]
	v_lshl_add_u64 v[14:15], s[4:5], 0, v[68:69]
	global_load_dwordx4 v[10:13], v[10:11], off
	s_nop 0
	global_load_dwordx4 v[14:17], v[14:15], off
	ds_read_b128 v[76:79], v83
	ds_read_b128 v[124:127], v83 offset:64
	ds_read_b128 v[134:137], v83 offset:128
	ds_read_b128 v[138:141], v83 offset:192
	ds_read_b128 v[142:145], v83 offset:4352
	ds_read_b128 v[146:149], v83 offset:4416
	ds_read_b128 v[150:153], v83 offset:4480
	ds_read_b128 v[154:157], v83 offset:4544
	ds_read_b128 v[158:161], v83 offset:8704
	ds_read_b128 v[162:165], v83 offset:8768
	ds_read_b128 v[166:169], v83 offset:8832
	ds_read_b128 v[170:173], v83 offset:8896
	ds_read_b128 v[174:177], v83 offset:13056
	ds_read_b128 v[178:181], v83 offset:13120
	ds_read_b128 v[182:185], v83 offset:13184
	ds_read_b128 v[186:189], v83 offset:13248
	s_waitcnt lgkmcnt(14)
	v_mfma_f32_16x16x32_bf16 v[76:79], v[76:79], v[18:21], 0
	v_add_u32_e32 v128, 0x4000, v116
	v_add_u32_e32 v133, 0x4000, v117
	v_add_u32_e32 v129, 0x8000, v114
	s_waitcnt lgkmcnt(11)
	v_mfma_f32_16x16x32_bf16 v[142:145], v[142:145], v[18:21], 0
	v_mfma_f32_16x16x32_bf16 v[76:79], v[124:127], v[22:25], v[76:79]
	s_waitcnt lgkmcnt(7)
	v_mfma_f32_16x16x32_bf16 v[158:161], v[158:161], v[18:21], 0
	v_mfma_f32_16x16x32_bf16 v[124:127], v[146:149], v[22:25], v[142:145]
	v_mfma_f32_16x16x32_bf16 v[76:79], v[134:137], v[26:29], v[76:79]
	s_waitcnt lgkmcnt(3)
	v_mfma_f32_16x16x32_bf16 v[174:177], v[174:177], v[18:21], 0
	v_mfma_f32_16x16x32_bf16 v[142:145], v[162:165], v[22:25], v[158:161]
	v_mfma_f32_16x16x32_bf16 v[124:127], v[150:153], v[26:29], v[124:127]
	s_nop 1
	ds_read_b128 v[160:163], v129 offset:768
	v_mfma_f32_16x16x32_bf16 v[76:79], v[138:141], v[30:33], v[76:79]
	v_mfma_f32_16x16x32_bf16 v[134:137], v[166:169], v[26:29], v[142:145]
	s_waitcnt lgkmcnt(3)
	v_mfma_f32_16x16x32_bf16 v[140:143], v[178:181], v[22:25], v[174:177]
	s_nop 4
	v_max_f32_e32 v75, v77, v77
	v_max_f32_e32 v80, v76, v76
	v_max_f32_e32 v75, v80, v75
	v_mfma_f32_16x16x32_bf16 v[124:127], v[154:157], v[30:33], v[124:127]
	v_max_f32_e32 v80, v79, v79
	v_max_f32_e32 v81, v78, v78
	v_max_f32_e32 v80, v81, v80
	s_waitcnt lgkmcnt(2)
	v_mfma_f32_16x16x32_bf16 v[140:143], v[182:185], v[26:29], v[140:143]
	v_max3_f32 v75, v75, v80, s76
	s_nop 1
	v_max_f32_e32 v80, v125, v125
	v_max_f32_e32 v81, v124, v124
	v_mfma_f32_16x16x32_bf16 v[136:139], v[170:173], v[30:33], v[134:137]
	v_max_f32_e32 v80, v81, v80
	v_max_f32_e32 v81, v127, v127
	v_max_f32_e32 v111, v126, v126
	v_max_f32_e32 v81, v111, v81
	s_waitcnt lgkmcnt(1)
	v_mfma_f32_16x16x32_bf16 v[140:143], v[186:189], v[30:33], v[140:143]
	v_max3_f32 v75, v80, v81, v75
	s_nop 0
	v_max_f32_e32 v80, v137, v137
	v_max_f32_e32 v81, v136, v136
	v_max_f32_e32 v80, v81, v80
	v_max_f32_e32 v81, v139, v139
	v_max_f32_e32 v111, v138, v138
	v_max_f32_e32 v81, v111, v81
	v_max3_f32 v75, v80, v81, v75
	v_max_f32_e32 v80, v141, v141
	v_max_f32_e32 v81, v140, v140
	v_max_f32_e32 v80, v81, v80
	v_max_f32_e32 v81, v143, v143
	v_max_f32_e32 v111, v142, v142
	v_max_f32_e32 v81, v111, v81
	v_max3_f32 v75, v80, v81, v75
	ds_bpermute_b32 v80, v85, v75
	v_add_u32_e32 v134, 0x4000, v114
	ds_read_b128 v[144:147], v133 offset:1024
	s_waitcnt lgkmcnt(1)
	v_max_f32_e32 v80, v80, v80
	v_max_f32_e32 v75, v75, v80
	ds_bpermute_b32 v80, v87, v75
	s_waitcnt lgkmcnt(0)
	v_max3_f32 v135, v0, v75, v80
	v_sub_f32_e32 v75, v76, v135
	v_exp_f32_e32 v75, v75
	v_sub_f32_e32 v76, v77, v135
	v_exp_f32_e32 v80, v76
	v_sub_f32_e32 v76, v78, v135
	v_exp_f32_e32 v81, v76
	v_sub_f32_e32 v76, v79, v135
	v_exp_f32_e32 v112, v76
	v_sub_f32_e32 v77, v124, v135
	v_add_f32_e32 v76, 0, v75
	v_exp_f32_e32 v113, v77
	v_sub_f32_e32 v77, v125, v135
	v_add_f32_e32 v76, v80, v76
	v_exp_f32_e32 v166, v77
	v_sub_f32_e32 v77, v126, v135
	v_add_f32_e32 v76, v81, v76
	v_exp_f32_e32 v167, v77
	v_sub_f32_e32 v77, v127, v135
	v_add_f32_e32 v76, v112, v76
	v_exp_f32_e32 v168, v77
	v_sub_f32_e32 v77, v136, v135
	v_add_f32_e32 v76, v113, v76
	v_exp_f32_e32 v169, v77
	v_sub_f32_e32 v77, v137, v135
	v_add_f32_e32 v76, v166, v76
	v_exp_f32_e32 v170, v77
	v_sub_f32_e32 v77, v138, v135
	v_add_f32_e32 v76, v167, v76
	v_exp_f32_e32 v171, v77
	v_sub_f32_e32 v77, v139, v135
	v_add_f32_e32 v76, v168, v76
	v_exp_f32_e32 v172, v77
	v_sub_f32_e32 v77, v140, v135
	v_add_f32_e32 v76, v169, v76
	v_exp_f32_e32 v173, v77
	v_sub_f32_e32 v77, v141, v135
	v_add_f32_e32 v76, v170, v76
	v_exp_f32_e32 v174, v77
	v_sub_f32_e32 v77, v142, v135
	v_add_f32_e32 v76, v171, v76
	v_exp_f32_e32 v175, v77
	v_sub_f32_e32 v77, v143, v135
	v_add_f32_e32 v76, v172, v76
	v_exp_f32_e32 v176, v77
	v_add_f32_e32 v76, v173, v76
	v_sub_f32_e32 v0, v0, v135
	v_add_f32_e32 v76, v174, v76
	v_exp_f32_e32 v0, v0
	v_add_f32_e32 v76, v175, v76
	v_add_u32_e32 v126, 0x4000, v115
	v_add_u32_e32 v124, 0x6800, v114
	v_add_u32_e32 v125, 0x7000, v114
	v_add_u32_e32 v127, 0x7800, v114
	v_add_f32_e32 v111, v176, v76
	ds_read_b128 v[76:79], v134 offset:1024
	ds_read_b128 v[136:139], v126 offset:1024
	ds_read_b128 v[140:143], v128 offset:1024
	ds_read_b128 v[148:151], v124
	ds_read_b128 v[152:155], v125 offset:256
	ds_read_b128 v[156:159], v127 offset:512
	v_pk_mul_f32 v[72:73], v[72:73], v[0:1] op_sel_hi:[1,0]
	v_pk_mul_f32 v[70:71], v[70:71], v[0:1] op_sel_hi:[1,0]
	v_pk_mul_f32 v[64:65], v[64:65], v[0:1] op_sel_hi:[1,0]
	v_pk_mul_f32 v[62:63], v[62:63], v[0:1] op_sel_hi:[1,0]
	v_pk_mul_f32 v[56:57], v[56:57], v[0:1] op_sel_hi:[1,0]
	v_pk_mul_f32 v[54:55], v[54:55], v[0:1] op_sel_hi:[1,0]
	v_pk_mul_f32 v[52:53], v[52:53], v[0:1] op_sel_hi:[1,0]
	v_pk_mul_f32 v[50:51], v[50:51], v[0:1] op_sel_hi:[1,0]
	v_pk_mul_f32 v[44:45], v[44:45], v[0:1] op_sel_hi:[1,0]
	v_pk_mul_f32 v[42:43], v[42:43], v[0:1] op_sel_hi:[1,0]
	v_pk_mul_f32 v[36:37], v[36:37], v[0:1] op_sel_hi:[1,0]
	v_pk_mul_f32 v[34:35], v[34:35], v[0:1] op_sel_hi:[1,0]
	v_pk_mul_f32 v[48:49], v[48:49], v[0:1] op_sel_hi:[1,0]
	v_pk_mul_f32 v[46:47], v[46:47], v[0:1] op_sel_hi:[1,0]
	v_pk_mul_f32 v[40:41], v[40:41], v[0:1] op_sel_hi:[1,0]
	v_pk_mul_f32 v[38:39], v[38:39], v[0:1] op_sel_hi:[1,0]
	v_cvt_pk_bf16_f32 v164, v75, v80
	v_cvt_pk_bf16_f32 v165, v81, v112
	v_cvt_pk_bf16_f32 v166, v113, v166
	v_cvt_pk_bf16_f32 v167, v167, v168
	s_waitcnt lgkmcnt(5)
	v_mfma_f32_16x16x32_bf16 v[70:73], v[76:79], v[164:167], v[70:73]
	v_cvt_pk_bf16_f32 v76, v169, v170
	v_cvt_pk_bf16_f32 v77, v171, v172
	v_cvt_pk_bf16_f32 v78, v173, v174
	s_waitcnt lgkmcnt(4)
	v_mfma_f32_16x16x32_bf16 v[62:65], v[136:139], v[164:167], v[62:65]
	v_cvt_pk_bf16_f32 v79, v175, v176
	s_waitcnt lgkmcnt(3)
	v_mfma_f32_16x16x32_bf16 v[54:57], v[140:143], v[164:167], v[54:57]
	v_mfma_f32_16x16x32_bf16 v[50:53], v[144:147], v[164:167], v[50:53]
	s_waitcnt lgkmcnt(2)
	v_mfma_f32_16x16x32_bf16 v[42:45], v[148:151], v[164:167], v[42:45]
	s_waitcnt lgkmcnt(1)
	v_mfma_f32_16x16x32_bf16 v[34:37], v[152:155], v[164:167], v[34:37]
	s_waitcnt lgkmcnt(0)
	v_mfma_f32_16x16x32_bf16 v[46:49], v[156:159], v[164:167], v[46:49]
	v_mfma_f32_16x16x32_bf16 v[38:41], v[160:163], v[164:167], v[38:41]
	ds_read_b128 v[136:139], v134 offset:1088
	ds_read_b128 v[140:143], v126 offset:1088
	ds_read_b128 v[144:147], v128 offset:1088
	ds_read_b128 v[148:151], v133 offset:1088
	ds_read_b128 v[152:155], v124 offset:64
	ds_read_b128 v[156:159], v125 offset:320
	ds_read_b128 v[160:163], v127 offset:576
	ds_read_b128 v[164:167], v129 offset:832
	s_waitcnt lgkmcnt(7)
	v_mfma_f32_16x16x32_bf16 v[70:73], v[136:139], v[76:79], v[70:73]
	s_add_i32 s18, s18, -1
	v_fmac_f32_e32 v111, v74, v0
	v_lshl_add_u64 v[58:59], v[58:59], 0, s[26:27]
	s_waitcnt lgkmcnt(6)
	v_mfma_f32_16x16x32_bf16 v[62:65], v[140:143], v[76:79], v[62:65]
	v_lshl_add_u64 v[60:61], v[60:61], 0, s[26:27]
	v_lshl_add_u64 v[66:67], v[66:67], 0, s[22:23]
	v_lshl_add_u64 v[68:69], v[68:69], 0, s[22:23]
	s_waitcnt lgkmcnt(5)
	v_mfma_f32_16x16x32_bf16 v[54:57], v[144:147], v[76:79], v[54:57]
	s_cmp_eq_u32 s18, 0
	s_waitcnt lgkmcnt(4)
	v_mfma_f32_16x16x32_bf16 v[50:53], v[148:151], v[76:79], v[50:53]
	s_waitcnt lgkmcnt(3)
	v_mfma_f32_16x16x32_bf16 v[42:45], v[152:155], v[76:79], v[42:45]
	s_waitcnt lgkmcnt(2)
	v_mfma_f32_16x16x32_bf16 v[34:37], v[156:159], v[76:79], v[34:37]
	s_waitcnt lgkmcnt(1)
	v_mfma_f32_16x16x32_bf16 v[46:49], v[160:163], v[76:79], v[46:49]
	s_waitcnt lgkmcnt(0)
	v_mfma_f32_16x16x32_bf16 v[38:41], v[164:167], v[76:79], v[38:41]
	s_cbranch_scc1 .LBB0_1835
	v_mov_b32_e32 v0, v135
	v_mov_b32_e32 v74, v111
	s_branch .LBB0_1825

.LBB0_1839:
	s_or_b64 exec, exec, s[16:17]
	s_andn2_b64 vcc, exec, s[14:15]
	s_waitcnt vmcnt(1)
	ds_write_b64 v118, v[10:11] offset:17408
	ds_write_b64 v118, v[12:13] offset:17424
	s_waitcnt vmcnt(0)
	ds_write_b64 v119, v[14:15] offset:17408
	ds_write_b64 v119, v[16:17] offset:17424
	s_waitcnt lgkmcnt(0)
	s_barrier
	s_cbranch_vccnz .LBB0_1853
	s_and_b32 s20, s13, 3
	s_ashr_i32 s13, s52, 31
	s_add_u32 s14, s52, s47
	s_addc_u32 s15, s13, 0
	s_lshl_b32 s13, s20, 15
	s_lshl_b64 s[14:15], s[14:15], 17
	s_or_b32 s14, s14, s13
	s_lshl_b64 s[14:15], s[14:15], 1
	s_add_u32 s16, s40, s14
	s_addc_u32 s17, s41, s15
	s_and_saveexec_b64 s[18:19], s[0:1]
	s_cbranch_execz .LBB0_1842
	v_lshl_add_u64 v[2:3], s[16:17], 0, v[98:99]
	v_lshl_add_u64 v[2:3], v[92:93], 1, v[2:3]
	global_load_dwordx4 v[2:5], v[2:3], off

.LBB0_1853:
.LBB0_1854:
	ds_read_b128 v[136:139], v83
	ds_read_b128 v[140:143], v83 offset:64
	ds_read_b128 v[144:147], v83 offset:128
	ds_read_b128 v[148:151], v83 offset:192
	ds_read_b128 v[152:155], v83 offset:4352
	ds_read_b128 v[156:159], v83 offset:4416
	ds_read_b128 v[160:163], v83 offset:4480
	ds_read_b128 v[164:167], v83 offset:4544
	ds_read_b128 v[168:171], v83 offset:8704
	ds_read_b128 v[172:175], v83 offset:8768
	ds_read_b128 v[176:179], v83 offset:8832
	ds_read_b128 v[180:183], v83 offset:8896
	ds_read_b128 v[184:187], v83 offset:13056
	ds_read_b128 v[188:191], v83 offset:13120
	ds_read_b128 v[192:195], v83 offset:13184
	ds_read_b128 v[196:199], v83 offset:13248
	s_waitcnt lgkmcnt(14)
	v_mfma_f32_16x16x32_bf16 v[136:139], v[136:139], v[18:21], 0
	s_waitcnt lgkmcnt(11)
	v_mfma_f32_16x16x32_bf16 v[152:155], v[152:155], v[18:21], 0
	v_mfma_f32_16x16x32_bf16 v[136:139], v[140:143], v[22:25], v[136:139]
	s_waitcnt lgkmcnt(7)
	v_mfma_f32_16x16x32_bf16 v[168:171], v[168:171], v[18:21], 0
	v_mfma_f32_16x16x32_bf16 v[140:143], v[156:159], v[22:25], v[152:155]
	s_waitcnt lgkmcnt(3)
	v_mfma_f32_16x16x32_bf16 v[18:21], v[184:187], v[18:21], 0
	v_mfma_f32_16x16x32_bf16 v[136:139], v[144:147], v[26:29], v[136:139]
	v_mfma_f32_16x16x32_bf16 v[152:155], v[172:175], v[22:25], v[168:171]
	v_mfma_f32_16x16x32_bf16 v[140:143], v[160:163], v[26:29], v[140:143]
	v_mfma_f32_16x16x32_bf16 v[136:139], v[148:151], v[30:33], v[136:139]
	s_waitcnt lgkmcnt(2)
	v_mfma_f32_16x16x32_bf16 v[18:21], v[188:191], v[22:25], v[18:21]
	v_mfma_f32_16x16x32_bf16 v[144:147], v[176:179], v[26:29], v[152:155]
	s_nop 4
	v_max_f32_e32 v0, v137, v137
	v_max_f32_e32 v112, v136, v136
	v_max_f32_e32 v0, v112, v0
	v_mfma_f32_16x16x32_bf16 v[140:143], v[164:167], v[30:33], v[140:143]
	v_max_f32_e32 v112, v139, v139
	v_max_f32_e32 v113, v138, v138
	v_max_f32_e32 v112, v113, v112
	s_waitcnt lgkmcnt(1)
	v_mfma_f32_16x16x32_bf16 v[18:21], v[192:195], v[26:29], v[18:21]
	v_max3_f32 v0, v0, v112, s76
	s_nop 1
	v_max_f32_e32 v112, v141, v141
	v_max_f32_e32 v113, v140, v140
	v_mfma_f32_16x16x32_bf16 v[144:147], v[180:183], v[30:33], v[144:147]
	v_max_f32_e32 v112, v113, v112
	v_max_f32_e32 v113, v143, v143
	v_max_f32_e32 v148, v142, v142
	s_waitcnt lgkmcnt(0)
	v_mfma_f32_16x16x32_bf16 v[18:21], v[196:199], v[30:33], v[18:21]
	v_max_f32_e32 v113, v148, v113
	v_max3_f32 v0, v112, v113, v0
	s_nop 0
	v_max_f32_e32 v112, v145, v145
	v_max_f32_e32 v22, v144, v144
	v_max_f32_e32 v23, v147, v147
	v_max_f32_e32 v24, v146, v146
	v_max_f32_e32 v22, v22, v112
	v_max_f32_e32 v23, v24, v23
	v_max3_f32 v0, v22, v23, v0
	v_max_f32_e32 v22, v19, v19
	v_max_f32_e32 v23, v18, v18
	v_max_f32_e32 v22, v23, v22
	v_max_f32_e32 v23, v21, v21
	v_max_f32_e32 v24, v20, v20
	v_max_f32_e32 v23, v24, v23
	v_max3_f32 v0, v22, v23, v0
	ds_bpermute_b32 v22, v85, v0
	s_waitcnt lgkmcnt(0)
	v_max_f32_e32 v22, v22, v22
	v_max_f32_e32 v0, v0, v22
	ds_bpermute_b32 v22, v87, v0
	s_waitcnt lgkmcnt(0)
	v_max3_f32 v22, v135, v0, v22
	v_sub_f32_e32 v23, v136, v22
	v_exp_f32_e32 v112, v23
	v_sub_f32_e32 v23, v137, v22
	v_exp_f32_e32 v113, v23
	v_sub_f32_e32 v23, v138, v22
	v_sub_f32_e32 v0, v135, v22
	v_exp_f32_e32 v135, v23
	v_sub_f32_e32 v23, v139, v22
	v_exp_f32_e32 v153, v23
	v_sub_f32_e32 v24, v140, v22
	v_add_f32_e32 v23, 0, v112
	v_exp_f32_e32 v154, v24
	v_sub_f32_e32 v24, v141, v22
	v_add_f32_e32 v23, v113, v23
	v_exp_f32_e32 v155, v24
	v_sub_f32_e32 v24, v142, v22
	v_add_f32_e32 v23, v135, v23
	v_exp_f32_e32 v156, v24
	v_sub_f32_e32 v24, v143, v22
	v_add_f32_e32 v23, v153, v23
	v_exp_f32_e32 v157, v24
	v_sub_f32_e32 v24, v144, v22
	v_add_f32_e32 v23, v154, v23
	v_exp_f32_e32 v158, v24
	v_sub_f32_e32 v24, v145, v22
	v_add_f32_e32 v23, v155, v23
	v_exp_f32_e32 v159, v24
	v_sub_f32_e32 v24, v146, v22
	v_add_f32_e32 v23, v156, v23
	v_exp_f32_e32 v160, v24
	v_sub_f32_e32 v24, v147, v22
	v_add_f32_e32 v23, v157, v23
	v_exp_f32_e32 v161, v24
	v_sub_f32_e32 v18, v18, v22
	v_add_f32_e32 v23, v158, v23
	v_exp_f32_e32 v162, v18
	v_sub_f32_e32 v18, v19, v22
	v_exp_f32_e32 v0, v0
	v_add_f32_e32 v23, v159, v23
	v_exp_f32_e32 v163, v18
	v_sub_f32_e32 v18, v20, v22
	v_add_f32_e32 v23, v160, v23
	v_exp_f32_e32 v164, v18
	v_sub_f32_e32 v18, v21, v22
	v_add_f32_e32 v136, v161, v23
	v_exp_f32_e32 v165, v18
	v_pk_mul_f32 v[30:31], v[50:51], v[0:1] op_sel_hi:[1,0]
	v_add_f32_e32 v50, v162, v136
	v_add_f32_e32 v50, v163, v50
	v_add_f32_e32 v50, v164, v50
	v_pk_mul_f32 v[20:21], v[72:73], v[0:1] op_sel_hi:[1,0]
	v_pk_mul_f32 v[18:19], v[70:71], v[0:1] op_sel_hi:[1,0]
	v_pk_mul_f32 v[24:25], v[64:65], v[0:1] op_sel_hi:[1,0]
	v_pk_mul_f32 v[22:23], v[62:63], v[0:1] op_sel_hi:[1,0]
	v_pk_mul_f32 v[28:29], v[56:57], v[0:1] op_sel_hi:[1,0]
	v_pk_mul_f32 v[26:27], v[54:55], v[0:1] op_sel_hi:[1,0]
	v_pk_mul_f32 v[32:33], v[52:53], v[0:1] op_sel_hi:[1,0]
	v_add_f32_e32 v166, v165, v50
	ds_read_b128 v[50:53], v134 offset:1024
	ds_read_b128 v[54:57], v126 offset:1024
	ds_read_b128 v[62:65], v128 offset:1024
	ds_read_b128 v[70:73], v133 offset:1024
	ds_read_b128 v[136:139], v124
	ds_read_b128 v[140:143], v125 offset:256
	ds_read_b128 v[144:147], v127 offset:512
	ds_read_b128 v[148:151], v129 offset:768
	v_pk_mul_f32 v[44:45], v[44:45], v[0:1] op_sel_hi:[1,0]
	v_pk_mul_f32 v[42:43], v[42:43], v[0:1] op_sel_hi:[1,0]
	v_pk_mul_f32 v[36:37], v[36:37], v[0:1] op_sel_hi:[1,0]
	v_pk_mul_f32 v[34:35], v[34:35], v[0:1] op_sel_hi:[1,0]
	v_pk_mul_f32 v[48:49], v[48:49], v[0:1] op_sel_hi:[1,0]
	v_pk_mul_f32 v[46:47], v[46:47], v[0:1] op_sel_hi:[1,0]
	v_pk_mul_f32 v[40:41], v[40:41], v[0:1] op_sel_hi:[1,0]
	v_pk_mul_f32 v[38:39], v[38:39], v[0:1] op_sel_hi:[1,0]
	v_cvt_pk_bf16_f32 v152, v112, v113
	v_cvt_pk_bf16_f32 v153, v135, v153
	v_cvt_pk_bf16_f32 v154, v154, v155
	v_cvt_pk_bf16_f32 v155, v156, v157
	s_waitcnt lgkmcnt(7)
	v_mfma_f32_16x16x32_bf16 v[18:21], v[50:53], v[152:155], v[18:21]
	s_waitcnt lgkmcnt(6)
	v_mfma_f32_16x16x32_bf16 v[22:25], v[54:57], v[152:155], v[22:25]
	s_waitcnt lgkmcnt(5)
	v_mfma_f32_16x16x32_bf16 v[26:29], v[62:65], v[152:155], v[26:29]
	s_waitcnt lgkmcnt(4)
	v_mfma_f32_16x16x32_bf16 v[30:33], v[70:73], v[152:155], v[30:33]
	s_waitcnt lgkmcnt(3)
	v_mfma_f32_16x16x32_bf16 v[50:53], v[136:139], v[152:155], v[42:45]
	v_cvt_pk_bf16_f32 v136, v158, v159
	v_cvt_pk_bf16_f32 v137, v160, v161
	v_cvt_pk_bf16_f32 v138, v162, v163
	s_waitcnt lgkmcnt(2)
	v_mfma_f32_16x16x32_bf16 v[54:57], v[140:143], v[152:155], v[34:37]
	v_cvt_pk_bf16_f32 v139, v164, v165
	s_waitcnt lgkmcnt(1)
	v_mfma_f32_16x16x32_bf16 v[62:65], v[144:147], v[152:155], v[46:49]
	s_waitcnt lgkmcnt(0)
	v_mfma_f32_16x16x32_bf16 v[70:73], v[148:151], v[152:155], v[38:41]
	ds_read_b128 v[34:37], v134 offset:1088
	s_nop 1
	ds_read_b128 v[38:41], v126 offset:1088
	ds_read_b128 v[140:143], v128 offset:1088
	ds_read_b128 v[144:147], v133 offset:1088
	ds_read_b128 v[148:151], v124 offset:64
	ds_read_b128 v[152:155], v125 offset:320
	ds_read_b128 v[124:127], v127 offset:576
	ds_read_b128 v[156:159], v129 offset:832
	v_fmac_f32_e32 v166, v111, v0
	ds_bpermute_b32 v0, v85, v166
	s_waitcnt lgkmcnt(8)
	v_mfma_f32_16x16x32_bf16 v[46:49], v[34:37], v[136:139], v[18:21]
	v_cmp_gt_i32_e32 vcc, s49, v82
	s_waitcnt lgkmcnt(0)
	v_add_f32_e32 v0, v166, v0
	v_mfma_f32_16x16x32_bf16 v[34:37], v[144:147], v[136:139], v[30:33]
	v_mfma_f32_16x16x32_bf16 v[30:33], v[148:151], v[136:139], v[50:53]
	s_nop 2
	ds_bpermute_b32 v50, v87, v0
	v_mfma_f32_16x16x32_bf16 v[42:45], v[38:41], v[136:139], v[22:25]
	v_mfma_f32_16x16x32_bf16 v[38:41], v[140:143], v[136:139], v[26:29]
	v_mfma_f32_16x16x32_bf16 v[26:29], v[152:155], v[136:139], v[54:57]
	v_mfma_f32_16x16x32_bf16 v[22:25], v[124:127], v[136:139], v[62:65]
	v_mfma_f32_16x16x32_bf16 v[18:21], v[156:159], v[136:139], v[70:73]
	s_and_saveexec_b64 s[12:13], vcc
	s_cbranch_execz .LBB0_1800
	s_lshl_b64 s[8:9], s[8:9], 1
	s_add_u32 s14, s44, s8
	s_waitcnt lgkmcnt(0)
	v_add_f32_e32 v0, v0, v50
	s_addc_u32 s15, s45, s9
	v_div_scale_f32 v50, s[8:9], v0, v0, 1.0
	v_rcp_f32_e32 v51, v50
	s_lshl_b32 s8, s50, 1
	s_add_u32 s8, s14, s8
	s_addc_u32 s9, s15, 0
	v_fma_f32 v52, -v50, v51, 1.0
	v_fmac_f32_e32 v51, v52, v51
	v_div_scale_f32 v52, vcc, 1.0, v0, 1.0
	v_mul_f32_e32 v53, v52, v51
	v_fma_f32 v54, -v50, v53, v52
	v_fmac_f32_e32 v53, v54, v51
	v_fma_f32 v50, -v50, v53, v52
	v_div_fmas_f32 v50, v50, v51, v53
	v_div_fixup_f32 v0, v50, v0, 1.0
	v_lshl_add_u64 v[50:51], s[8:9], 0, v[96:97]
	v_mov_b32_e32 v111, v1
	v_mul_f32_e32 v46, v46, v0
	v_mul_f32_e32 v47, v47, v0
	v_mul_f32_e32 v42, v42, v0
	v_mul_f32_e32 v43, v43, v0
	v_mul_f32_e32 v38, v38, v0
	v_mul_f32_e32 v39, v39, v0
	v_mul_f32_e32 v34, v34, v0
	v_mul_f32_e32 v35, v35, v0
	v_mul_f32_e32 v30, v30, v0
	v_mul_f32_e32 v31, v31, v0
	v_mul_f32_e32 v26, v26, v0
	v_mul_f32_e32 v27, v27, v0
	v_mul_f32_e32 v22, v22, v0
	v_mul_f32_e32 v23, v23, v0
	v_mul_f32_e32 v18, v18, v0
	v_mul_f32_e32 v19, v19, v0
	v_lshl_add_u64 v[50:51], v[50:51], 0, v[110:111]
	v_cvt_pk_bf16_f32 v46, v46, v47
	v_mul_f32_e32 v47, v48, v0
	v_cvt_pk_bf16_f32 v42, v42, v43
	v_mul_f32_e32 v43, v44, v0
	v_cvt_pk_bf16_f32 v38, v38, v39
	v_mul_f32_e32 v39, v40, v0
	v_cvt_pk_bf16_f32 v34, v34, v35
	v_mul_f32_e32 v35, v36, v0
	v_cvt_pk_bf16_f32 v30, v30, v31
	v_mul_f32_e32 v31, v32, v0
	v_cvt_pk_bf16_f32 v26, v26, v27
	v_mul_f32_e32 v27, v28, v0
	v_cvt_pk_bf16_f32 v22, v22, v23
	v_mul_f32_e32 v23, v24, v0
	v_cvt_pk_bf16_f32 v18, v18, v19
	v_mul_f32_e32 v19, v20, v0
	v_mul_f32_e32 v48, v49, v0
	v_cvt_pk_bf16_f32 v47, v47, v48
	global_store_dwordx2 v[50:51], v[46:47], off
	v_mul_f32_e32 v44, v45, v0
	v_cvt_pk_bf16_f32 v43, v43, v44
	global_store_dwordx2 v[50:51], v[42:43], off offset:32
	v_mul_f32_e32 v40, v41, v0
	v_cvt_pk_bf16_f32 v39, v39, v40
	global_store_dwordx2 v[50:51], v[38:39], off offset:64
	v_mul_f32_e32 v36, v37, v0
	v_cvt_pk_bf16_f32 v35, v35, v36
	global_store_dwordx2 v[50:51], v[34:35], off offset:96
	v_mul_f32_e32 v32, v33, v0
	v_cvt_pk_bf16_f32 v31, v31, v32
	global_store_dwordx2 v[50:51], v[30:31], off offset:128
	v_mul_f32_e32 v28, v29, v0
	v_cvt_pk_bf16_f32 v27, v27, v28
	global_store_dwordx2 v[50:51], v[26:27], off offset:160
	v_mul_f32_e32 v24, v25, v0
	v_cvt_pk_bf16_f32 v23, v23, v24
	global_store_dwordx2 v[50:51], v[22:23], off offset:192
	v_mul_f32_e32 v0, v21, v0
	v_cvt_pk_bf16_f32 v19, v19, v0
	global_store_dwordx2 v[50:51], v[18:19], off offset:224
	s_branch .LBB0_1800
